# attention: bias pairs of a local-window group read up front; G2 final-merge gate loads hoisted; staging batched; scan slot pairing
# baseline (speedup 1.0000x reference)
.LBB0_726:
	s_and_b64 vcc, exec, s[24:25]
	s_cbranch_vccz .LBB0_730
	v_add_u32_e32 v212, 0x1e1b0, v173
	ds_read2_b32 v[180:181], v212 offset0:0 offset1:1
	ds_read2_b32 v[182:183], v212 offset0:2 offset1:3
	ds_read2_b32 v[184:185], v212 offset0:8 offset1:9
	ds_read2_b32 v[186:187], v212 offset0:10 offset1:11
	ds_read2_b32 v[188:189], v212 offset0:16 offset1:17
	ds_read2_b32 v[190:191], v212 offset0:18 offset1:19
	ds_read2_b32 v[192:193], v212 offset0:24 offset1:25
	ds_read2_b32 v[194:195], v212 offset0:26 offset1:27
	ds_read2_b32 v[196:197], v212 offset0:32 offset1:33
	ds_read2_b32 v[198:199], v212 offset0:34 offset1:35
	ds_read2_b32 v[200:201], v212 offset0:40 offset1:41
	ds_read2_b32 v[202:203], v212 offset0:42 offset1:43
	ds_read2_b32 v[204:205], v212 offset0:48 offset1:49
	ds_read2_b32 v[206:207], v212 offset0:50 offset1:51
	ds_read2_b32 v[208:209], v212 offset0:56 offset1:57
	ds_read2_b32 v[210:211], v212 offset0:58 offset1:59
	s_waitcnt vmcnt(7)
	v_mfma_f32_32x32x16_bf16 v[18:33], v[82:85], v[66:69], 0
	s_cmp_eq_u64 s[14:15], 0
	s_waitcnt vmcnt(3)
	v_mfma_f32_32x32x16_bf16 v[2:17], v[98:101], v[66:69], 0
	v_mfma_f32_32x32x16_bf16 v[18:33], v[86:89], v[70:73], v[18:33]
	s_waitcnt vmcnt(2)
	v_mfma_f32_32x32x16_bf16 v[2:17], v[102:105], v[70:73], v[2:17]
	v_mfma_f32_32x32x16_bf16 v[18:33], v[90:93], v[74:77], v[18:33]
	s_waitcnt vmcnt(1)
	v_mfma_f32_32x32x16_bf16 v[2:17], v[106:109], v[74:77], v[2:17]
	v_mfma_f32_32x32x16_bf16 v[18:33], v[94:97], v[78:81], v[18:33]
	s_waitcnt vmcnt(0)
	v_mfma_f32_32x32x16_bf16 v[2:17], v[110:113], v[78:81], v[2:17]
	s_cbranch_scc1 .LBB0_729
	v_mul_u32_u24_e32 v0, s8, v157
	v_lshlrev_b32_e32 v0, 1, v0
	v_lshl_add_u64 v[82:83], s[14:15], 0, v[0:1]
	v_lshl_add_u64 v[98:99], v[152:153], 1, v[82:83]
	s_lshl_b32 s8, s8, 6
	s_mov_b32 s9, s17
	v_lshl_add_u64 v[110:111], v[98:99], 0, s[8:9]
	global_load_dwordx4 v[82:85], v[98:99], off
	global_load_dwordx4 v[86:89], v[98:99], off offset:32
	global_load_dwordx4 v[90:93], v[98:99], off offset:64
	global_load_dwordx4 v[94:97], v[98:99], off offset:96
	s_nop 0
	global_load_dwordx4 v[98:101], v[110:111], off
	global_load_dwordx4 v[102:105], v[110:111], off offset:32
	global_load_dwordx4 v[106:109], v[110:111], off offset:64
	s_nop 0
	global_load_dwordx4 v[110:113], v[110:111], off offset:96
.LBB0_729:
	s_waitcnt lgkmcnt(0)
	s_nop 11
	s_nop 4
	v_fmamk_f32 v0, v18, 0x3e38aa3b, v180
	v_fmac_f32_e32 v181, 0x3e38aa3b, v19
	v_cndmask_b32_e64 v18, v238, v0, s[34:35]
	v_cndmask_b32_e64 v0, v238, v181, s[36:37]
	v_max3_f32 v115, v18, s10, v0
	v_fmamk_f32 v19, v20, 0x3e38aa3b, v182
	v_fmac_f32_e32 v183, 0x3e38aa3b, v21
	v_cndmask_b32_e64 v20, v238, v19, s[38:39]
	v_cndmask_b32_e64 v19, v238, v183, s[40:41]
	v_max3_f32 v115, v115, v20, v19
	v_fmamk_f32 v21, v22, 0x3e38aa3b, v184
	v_fmac_f32_e32 v185, 0x3e38aa3b, v23
	v_cndmask_b32_e64 v22, v238, v21, s[42:43]
	v_cndmask_b32_e64 v21, v238, v185, s[44:45]
	v_max3_f32 v23, v115, v22, v21
	v_fmamk_f32 v24, v24, 0x3e38aa3b, v186
	v_fmac_f32_e32 v187, 0x3e38aa3b, v25
	v_cndmask_b32_e64 v115, v238, v24, s[46:47]
	v_cndmask_b32_e64 v25, v238, v187, s[48:49]
	v_max3_f32 v118, v23, v115, v25
	v_fmamk_f32 v23, v26, 0x3e38aa3b, v188
	v_fmac_f32_e32 v189, 0x3e38aa3b, v27
	v_cndmask_b32_e64 v24, v238, v23, s[50:51]
	v_cndmask_b32_e64 v23, v238, v189, s[52:53]
	v_max3_f32 v118, v118, v24, v23
	v_fmamk_f32 v26, v28, 0x3e38aa3b, v190
	v_fmac_f32_e32 v191, 0x3e38aa3b, v29
	v_cndmask_b32_e64 v27, v238, v26, s[54:55]
	v_cndmask_b32_e64 v26, v238, v191, s[56:57]
	v_max3_f32 v118, v118, v27, v26
	v_fmamk_f32 v28, v30, 0x3e38aa3b, v192
	v_fmac_f32_e32 v193, 0x3e38aa3b, v31
	v_cndmask_b32_e64 v29, v238, v28, s[58:59]
	v_cndmask_b32_e64 v28, v238, v193, s[60:61]
	v_max3_f32 v116, v118, v29, v28
	v_fmamk_f32 v30, v32, 0x3e38aa3b, v194
	v_cndmask_b32_e64 v32, v238, v30, s[62:63]
	v_fmac_f32_e32 v195, 0x3e38aa3b, v33
	v_cndmask_b32_e64 v33, v238, v195, s[64:65]
	v_max3_f32 v116, v116, v32, v33
	v_fmamk_f32 v2, v2, 0x3e38aa3b, v196
	v_cndmask_b32_e64 v30, v238, v2, s[66:67]
	v_fmac_f32_e32 v197, 0x3e38aa3b, v3
	v_cndmask_b32_e64 v31, v238, v197, s[68:69]
	v_max3_f32 v116, v116, v30, v31
	v_fmamk_f32 v2, v4, 0x3e38aa3b, v198
	v_cndmask_b32_e64 v4, v238, v2, s[70:71]
	v_fmac_f32_e32 v199, 0x3e38aa3b, v5
	v_cndmask_b32_e64 v5, v238, v199, s[72:73]
	v_max3_f32 v116, v116, v4, v5
	v_fmamk_f32 v2, v6, 0x3e38aa3b, v200
	v_cndmask_b32_e64 v6, v238, v2, s[74:75]
	v_fmac_f32_e32 v201, 0x3e38aa3b, v7
	v_cndmask_b32_e64 v7, v238, v201, s[76:77]
	v_max3_f32 v116, v116, v6, v7
	v_fmamk_f32 v2, v8, 0x3e38aa3b, v202
	v_cndmask_b32_e64 v8, v238, v2, s[78:79]
	v_fmac_f32_e32 v203, 0x3e38aa3b, v9
	v_cndmask_b32_e64 v9, v238, v203, s[80:81]
	v_max3_f32 v116, v116, v8, v9
	v_fmamk_f32 v2, v10, 0x3e38aa3b, v204
	v_cndmask_b32_e64 v10, v238, v2, s[82:83]
	v_fmac_f32_e32 v205, 0x3e38aa3b, v11
	v_cndmask_b32_e64 v11, v238, v205, s[84:85]
	v_max3_f32 v116, v116, v10, v11
	v_fmamk_f32 v2, v12, 0x3e38aa3b, v206
	v_cndmask_b32_e64 v12, v238, v2, s[86:87]
	v_fmac_f32_e32 v207, 0x3e38aa3b, v13
	v_cndmask_b32_e64 v13, v238, v207, s[88:89]
	v_max3_f32 v116, v116, v12, v13
	v_fmamk_f32 v2, v14, 0x3e38aa3b, v208
	v_cndmask_b32_e64 v14, v238, v2, s[90:91]
	v_fmac_f32_e32 v209, 0x3e38aa3b, v15
	v_cndmask_b32_e64 v15, v238, v209, s[92:93]
	v_max3_f32 v116, v116, v14, v15
	v_fmamk_f32 v2, v16, 0x3e38aa3b, v210
	v_fmac_f32_e32 v211, 0x3e38aa3b, v17
	v_cndmask_b32_e64 v2, v238, v2, s[94:95]
	v_cndmask_b32_e64 v3, v238, v211, s[96:97]
	v_max3_f32 v16, v116, v2, v3
	ds_bpermute_b32 v17, v165, v16
	s_waitcnt lgkmcnt(0)
	v_max3_f32 v177, v178, v16, v17
	v_sub_f32_e32 v17, v18, v177
	v_exp_f32_e32 v126, v17
	v_sub_f32_e32 v0, v0, v177
	v_exp_f32_e32 v127, v0
	v_sub_f32_e32 v4, v4, v177
	v_add_f32_e32 v17, 0, v126
	v_exp_f32_e32 v124, v4
	v_add_f32_e32 v0, v127, v17
	v_sub_f32_e32 v17, v20, v177
	v_exp_f32_e32 v128, v17
	v_sub_f32_e32 v17, v19, v177
	v_exp_f32_e32 v129, v17
	v_sub_f32_e32 v17, v22, v177
	v_exp_f32_e32 v130, v17
	v_sub_f32_e32 v17, v21, v177
	v_exp_f32_e32 v131, v17
	v_sub_f32_e32 v17, v115, v177
	v_add_f32_e32 v0, v128, v0
	v_exp_f32_e32 v132, v17
	v_sub_f32_e32 v17, v25, v177
	v_add_f32_e32 v0, v129, v0
	v_exp_f32_e32 v133, v17
	v_sub_f32_e32 v17, v24, v177
	v_add_f32_e32 v0, v130, v0
	v_exp_f32_e32 v134, v17
	v_sub_f32_e32 v17, v23, v177
	v_add_f32_e32 v0, v131, v0
	v_exp_f32_e32 v135, v17
	v_sub_f32_e32 v17, v27, v177
	v_add_f32_e32 v0, v132, v0
	v_exp_f32_e32 v136, v17
	v_sub_f32_e32 v17, v26, v177
	v_add_f32_e32 v0, v133, v0
	v_exp_f32_e32 v137, v17
	v_sub_f32_e32 v17, v29, v177
	v_add_f32_e32 v0, v134, v0
	v_exp_f32_e32 v138, v17
	v_sub_f32_e32 v17, v28, v177
	v_add_f32_e32 v0, v135, v0
	v_exp_f32_e32 v139, v17
	v_sub_f32_e32 v17, v32, v177
	v_add_f32_e32 v0, v136, v0
	v_exp_f32_e32 v140, v17
	v_sub_f32_e32 v17, v33, v177
	v_add_f32_e32 v0, v137, v0
	v_exp_f32_e32 v141, v17
	v_sub_f32_e32 v17, v30, v177
	v_add_f32_e32 v0, v138, v0
	v_exp_f32_e32 v122, v17
	v_sub_f32_e32 v17, v31, v177
	v_add_f32_e32 v0, v139, v0
	v_exp_f32_e32 v123, v17
	v_add_f32_e32 v0, v140, v0
	v_sub_f32_e32 v4, v5, v177
	v_add_f32_e32 v0, v141, v0
	v_exp_f32_e32 v125, v4
	v_sub_f32_e32 v4, v6, v177
	v_add_f32_e32 v0, v122, v0
	v_exp_f32_e32 v142, v4
	v_sub_f32_e32 v4, v7, v177
	v_sub_f32_e32 v16, v178, v177
	v_add_f32_e32 v0, v123, v0
	v_exp_f32_e32 v143, v4
	v_sub_f32_e32 v4, v8, v177
	v_add_f32_e32 v0, v124, v0
	v_exp_f32_e32 v144, v4
	v_sub_f32_e32 v4, v9, v177
	v_exp_f32_e32 v18, v16
	v_add_f32_e32 v0, v125, v0
	v_exp_f32_e32 v145, v4
	v_sub_f32_e32 v4, v10, v177
	v_add_f32_e32 v0, v142, v0
	v_exp_f32_e32 v114, v4
	v_sub_f32_e32 v4, v11, v177
	v_add_f32_e32 v0, v143, v0
	v_exp_f32_e32 v115, v4
	v_sub_f32_e32 v4, v12, v177
	v_add_f32_e32 v0, v144, v0
	v_exp_f32_e32 v116, v4
	v_sub_f32_e32 v4, v13, v177
	v_pk_mul_f32 v[26:27], v[42:43], v[18:19] op_sel_hi:[1,0]
	v_add_u32_e32 v42, 0, v174
	v_add_f32_e32 v0, v145, v0
	v_exp_f32_e32 v117, v4
	v_sub_f32_e32 v4, v14, v177
	v_pk_mul_f32 v[24:25], v[40:41], v[18:19] op_sel_hi:[1,0]
	v_pk_mul_f32 v[22:23], v[38:39], v[18:19] op_sel_hi:[1,0]
	v_add_u32_e32 v38, 0xffff8000, v42
	v_add_u32_e32 v40, 0xffff8400, v42
	v_add_f32_e32 v0, v114, v0
	v_exp_f32_e32 v118, v4
	v_sub_f32_e32 v4, v15, v177
	ds_read_b64_tr_b16 v[38:39], v38
	ds_read_b64_tr_b16 v[40:41], v40
	v_add_f32_e32 v0, v115, v0
	v_exp_f32_e32 v119, v4
	v_sub_f32_e32 v2, v2, v177
	v_add_f32_e32 v0, v116, v0
	v_exp_f32_e32 v120, v2
	v_sub_f32_e32 v2, v3, v177
	v_add_f32_e32 v0, v117, v0
	v_exp_f32_e32 v121, v2
	v_add_f32_e32 v0, v118, v0
	v_add_f32_e32 v0, v119, v0
	v_add_f32_e32 v0, v120, v0
	v_add_f32_e32 v0, v121, v0
	v_fmac_f32_e32 v0, v176, v18
	v_pk_mul_f32 v[16:17], v[64:65], v[18:19] op_sel_hi:[1,0]
	v_pk_mul_f32 v[14:15], v[62:63], v[18:19] op_sel_hi:[1,0]
	v_pk_mul_f32 v[12:13], v[60:61], v[18:19] op_sel_hi:[1,0]
	v_pk_mul_f32 v[10:11], v[58:59], v[18:19] op_sel_hi:[1,0]
	v_pk_mul_f32 v[8:9], v[56:57], v[18:19] op_sel_hi:[1,0]
	v_pk_mul_f32 v[6:7], v[54:55], v[18:19] op_sel_hi:[1,0]
	v_pk_mul_f32 v[4:5], v[52:53], v[18:19] op_sel_hi:[1,0]
	v_pk_mul_f32 v[2:3], v[50:51], v[18:19] op_sel_hi:[1,0]
	v_pk_mul_f32 v[32:33], v[48:49], v[18:19] op_sel_hi:[1,0]
	v_pk_mul_f32 v[30:31], v[46:47], v[18:19] op_sel_hi:[1,0]
	v_pk_mul_f32 v[28:29], v[44:45], v[18:19] op_sel_hi:[1,0]
	v_pk_mul_f32 v[20:21], v[36:37], v[18:19] op_sel_hi:[1,0]
	v_pk_mul_f32 v[18:19], v[34:35], v[18:19] op_sel_hi:[1,0]
	v_cvt_pk_bf16_f32 v34, v126, v127
	v_cvt_pk_bf16_f32 v35, v128, v129
	v_cvt_pk_bf16_f32 v36, v130, v131
	v_cvt_pk_bf16_f32 v37, v132, v133
	s_waitcnt vmcnt(4)
	v_mov_b64_e32 v[128:129], v[96:97]
	s_waitcnt vmcnt(3)
	v_mov_b64_e32 v[132:133], v[100:101]
	s_waitcnt lgkmcnt(0)
	v_mfma_f32_32x32x16_bf16 v[2:17], v[38:41], v[34:37], v[2:17]
	v_add_u32_e32 v38, 0xffff8040, v42
	v_add_u32_e32 v40, 0xffff8440, v42
	ds_read_b64_tr_b16 v[38:39], v38
	ds_read_b64_tr_b16 v[40:41], v40
	v_mov_b64_e32 v[126:127], v[94:95]
	v_mov_b64_e32 v[130:131], v[98:99]
	s_waitcnt lgkmcnt(0)
	v_mfma_f32_32x32x16_bf16 v[18:33], v[38:41], v[34:37], v[18:33]
	v_add_u32_e32 v38, 0xffff8800, v42
	v_add_u32_e32 v40, 0xffff8c00, v42
	ds_read_b64_tr_b16 v[38:39], v38
	ds_read_b64_tr_b16 v[40:41], v40
	v_cvt_pk_bf16_f32 v34, v134, v135
	v_cvt_pk_bf16_f32 v35, v136, v137
	v_cvt_pk_bf16_f32 v36, v138, v139
	v_cvt_pk_bf16_f32 v37, v140, v141
	s_waitcnt vmcnt(2)
	v_mov_b64_e32 v[136:137], v[104:105]
	s_waitcnt vmcnt(1)
	v_mov_b64_e32 v[140:141], v[108:109]
	s_waitcnt lgkmcnt(0)
	v_mfma_f32_32x32x16_bf16 v[2:17], v[38:41], v[34:37], v[2:17]
	v_add_u32_e32 v38, 0xffff8840, v42
	v_add_u32_e32 v40, 0xffff8c40, v42
	ds_read_b64_tr_b16 v[38:39], v38
	ds_read_b64_tr_b16 v[40:41], v40
	v_mov_b64_e32 v[134:135], v[102:103]
	v_mov_b64_e32 v[138:139], v[106:107]
	s_waitcnt lgkmcnt(0)
	v_mfma_f32_32x32x16_bf16 v[18:33], v[38:41], v[34:37], v[18:33]
	v_add_u32_e32 v38, 0xffff9000, v42
	v_add_u32_e32 v40, 0xffff9400, v42
	ds_read_b64_tr_b16 v[38:39], v38
	ds_read_b64_tr_b16 v[40:41], v40
	v_cvt_pk_bf16_f32 v34, v122, v123
	v_cvt_pk_bf16_f32 v35, v124, v125
	v_cvt_pk_bf16_f32 v36, v142, v143
	v_cvt_pk_bf16_f32 v37, v144, v145
	v_mov_b64_e32 v[124:125], v[92:93]
	s_waitcnt vmcnt(0)
	v_mov_b64_e32 v[144:145], v[112:113]
	s_waitcnt lgkmcnt(0)
	v_mfma_f32_32x32x16_bf16 v[2:17], v[38:41], v[34:37], v[2:17]
	v_add_u32_e32 v38, 0xffff9040, v42
	v_add_u32_e32 v40, 0xffff9440, v42
	ds_read_b64_tr_b16 v[38:39], v38
	ds_read_b64_tr_b16 v[40:41], v40
	v_mov_b64_e32 v[122:123], v[90:91]
	v_mov_b64_e32 v[142:143], v[110:111]
	s_waitcnt lgkmcnt(0)
	v_mfma_f32_32x32x16_bf16 v[18:33], v[38:41], v[34:37], v[18:33]
	v_add_u32_e32 v38, 0xffff9800, v42
	v_add_u32_e32 v40, 0xffff9c00, v42
	ds_read_b64_tr_b16 v[38:39], v38
	ds_read_b64_tr_b16 v[40:41], v40
	v_cvt_pk_bf16_f32 v34, v114, v115
	v_cvt_pk_bf16_f32 v35, v116, v117
	v_cvt_pk_bf16_f32 v36, v118, v119
	v_cvt_pk_bf16_f32 v37, v120, v121
	v_mov_b64_e32 v[116:117], v[84:85]
	v_mov_b64_e32 v[120:121], v[88:89]
	s_waitcnt lgkmcnt(0)
	v_mfma_f32_32x32x16_bf16 v[2:17], v[38:41], v[34:37], v[2:17]
	v_add_u32_e32 v38, 0xffff9840, v42
	v_add_u32_e32 v40, 0xffff9c40, v42
	ds_read_b64_tr_b16 v[38:39], v38
	ds_read_b64_tr_b16 v[40:41], v40
	v_mov_b64_e32 v[114:115], v[82:83]
	v_mov_b64_e32 v[118:119], v[86:87]
	s_waitcnt lgkmcnt(0)
	v_mfma_f32_32x32x16_bf16 v[18:33], v[38:41], v[34:37], v[18:33]

.LBB0_1236:
	v_mov_b32_e32 v0, v234
	s_lshl_b32 s0, s10, 8
	s_add_i32 s0, s0, s46
	v_and_or_b32 v136, v0, 15, s0
	s_lshl_b32 s0, s11, 8
	v_lshrrev_b32_e32 v0, 1, v0
	v_mov_b64_e32 v[2:3], s[66:67]
	v_and_or_b32 v0, v0, 24, s0
	v_mad_i64_i32 v[2:3], s[0:1], v136, s29, v[2:3]
	s_lshl_b32 s0, s54, 11
	v_or_b32_e32 v132, s47, v0
	s_ashr_i32 s1, s0, 31
	v_lshl_add_u64 v[2:3], s[0:1], 1, v[2:3]
	v_ashrrev_i32_e32 v133, 31, v132
	v_lshl_add_u64 v[2:3], v[132:133], 1, v[2:3]
	s_mov_b64 s[0:1], 0x4800
	v_lshl_add_u64 v[2:3], v[2:3], 0, s[0:1]
	s_cmp_gt_i32 s54, 1
	s_mov_b64 s[0:1], -1
	s_mov_b32 s6, 0x90000
	s_mov_b32 s7, 0xa0000
	s_mov_b32 s8, 0xb0000
	s_cbranch_scc0 .LBB0_1239
	global_load_dwordx4 v[156:159], v[2:3], off
	global_load_dwordx4 v[160:163], v[2:3], off offset:256
	s_mov_b64 s[98:99], 0x7c000
	v_lshl_add_u64 v[250:251], v[2:3], 0, s[98:99]
	global_load_dwordx4 v[164:167], v[250:251], off
	global_load_dwordx4 v[168:171], v[250:251], off offset:256
	s_mov_b64 s[98:99], 0xf8000
	v_lshl_add_u64 v[250:251], v[2:3], 0, s[98:99]
	global_load_dwordx4 v[172:175], v[250:251], off
	global_load_dwordx4 v[176:179], v[250:251], off offset:256
	s_mov_b64 s[98:99], 0x174000
	v_lshl_add_u64 v[250:251], v[2:3], 0, s[98:99]
	global_load_dwordx4 v[180:183], v[250:251], off
	global_load_dwordx4 v[184:187], v[250:251], off offset:256
	s_mov_b64 s[98:99], 0x3e0000
	v_lshl_add_u64 v[250:251], v[2:3], 0, s[98:99]
	global_load_dwordx4 v[188:191], v[250:251], off
	global_load_dwordx4 v[192:195], v[250:251], off offset:256
	s_mov_b64 s[98:99], 0x45c000
	v_lshl_add_u64 v[250:251], v[2:3], 0, s[98:99]
	global_load_dwordx4 v[210:213], v[250:251], off
	global_load_dwordx4 v[214:217], v[250:251], off offset:256
	s_mov_b64 s[98:99], 0x4d8000
	v_lshl_add_u64 v[250:251], v[2:3], 0, s[98:99]
	global_load_dwordx4 v[228:231], v[250:251], off
	global_load_dwordx4 v[242:245], v[250:251], off offset:256
	s_mov_b64 s[98:99], 0x554000
	v_lshl_add_u64 v[250:251], v[2:3], 0, s[98:99]
	global_load_dwordx4 v[246:249], v[250:251], off
	v_ashrrev_i32_e32 v137, 31, v136
	v_lshlrev_b64 v[134:135], 12, v[136:137]
	s_mov_b32 s0, 0x7c000
	s_waitcnt vmcnt(0)
	v_lshlrev_b32_e32 v0, 16, v156
	v_max_f32_e32 v0, v0, v0
	v_max_f32_e32 v142, 0x1e3ce508, v0
	v_and_b32_e32 v0, 0xffff0000, v156
	v_max_f32_e32 v0, v0, v0
	v_max_f32_e32 v143, 0x1e3ce508, v0
	v_lshlrev_b32_e32 v0, 16, v157
	v_max_f32_e32 v0, v0, v0
	v_max_f32_e32 v138, 0x1e3ce508, v0
	v_and_b32_e32 v0, 0xffff0000, v157
	v_max_f32_e32 v0, v0, v0
	v_max_f32_e32 v139, 0x1e3ce508, v0
	v_lshlrev_b32_e32 v0, 16, v158
	v_max_f32_e32 v0, v0, v0
	v_pk_mul_f32 v[144:145], v[130:131], v[138:139]
	v_max_f32_e32 v138, 0x1e3ce508, v0
	v_and_b32_e32 v0, 0xffff0000, v158
	v_max_f32_e32 v0, v0, v0
	v_max_f32_e32 v139, 0x1e3ce508, v0
	v_lshlrev_b32_e32 v0, 16, v159
	v_max_f32_e32 v0, v0, v0
	v_pk_mul_f32 v[146:147], v[124:125], v[138:139]
	v_max_f32_e32 v138, 0x1e3ce508, v0
	v_and_b32_e32 v0, 0xffff0000, v159
	v_max_f32_e32 v0, v0, v0
	v_pk_mul_f32 v[142:143], v[128:129], v[142:143]
	v_max_f32_e32 v139, 0x1e3ce508, v0
	v_pk_mul_f32 v[148:149], v[126:127], v[138:139]
	v_cvt_pk_bf16_f32 v138, v142, v143
	v_lshl_add_u64 v[142:143], s[64:65], 0, v[134:135]
	v_lshlrev_b64 v[134:135], 1, v[132:133]
	v_cvt_pk_bf16_f32 v139, v144, v145
	v_cvt_pk_bf16_f32 v140, v146, v147
	v_cvt_pk_bf16_f32 v141, v148, v149
	v_lshl_add_u64 v[132:133], v[142:143], 0, v[134:135]
	global_load_dwordx4 v[156:159], v[250:251], off offset:256
	global_store_dwordx4 v[132:133], v[138:141], off
	s_nop 1
	v_lshlrev_b32_e32 v0, 16, v160
	v_max_f32_e32 v0, v0, v0
	v_max_f32_e32 v142, 0x1e3ce508, v0
	v_and_b32_e32 v0, 0xffff0000, v160
	v_max_f32_e32 v0, v0, v0
	v_max_f32_e32 v143, 0x1e3ce508, v0
	v_lshlrev_b32_e32 v0, 16, v161
	v_max_f32_e32 v0, v0, v0
	v_max_f32_e32 v138, 0x1e3ce508, v0
	v_and_b32_e32 v0, 0xffff0000, v161
	v_max_f32_e32 v0, v0, v0
	v_max_f32_e32 v139, 0x1e3ce508, v0
	v_lshlrev_b32_e32 v0, 16, v162
	v_max_f32_e32 v0, v0, v0
	v_pk_mul_f32 v[144:145], v[98:99], v[138:139]
	v_max_f32_e32 v138, 0x1e3ce508, v0
	v_and_b32_e32 v0, 0xffff0000, v162
	v_max_f32_e32 v0, v0, v0
	v_max_f32_e32 v139, 0x1e3ce508, v0
	v_lshlrev_b32_e32 v0, 16, v163
	v_max_f32_e32 v0, v0, v0
	v_pk_mul_f32 v[146:147], v[92:93], v[138:139]
	v_max_f32_e32 v138, 0x1e3ce508, v0
	v_and_b32_e32 v0, 0xffff0000, v163
	v_max_f32_e32 v0, v0, v0
	v_max_f32_e32 v139, 0x1e3ce508, v0
	v_pk_mul_f32 v[142:143], v[96:97], v[142:143]
	v_pk_mul_f32 v[148:149], v[94:95], v[138:139]
	v_cvt_pk_bf16_f32 v138, v142, v143
	v_cvt_pk_bf16_f32 v139, v144, v145
	v_cvt_pk_bf16_f32 v140, v146, v147
	v_cvt_pk_bf16_f32 v141, v148, v149
	global_store_dwordx4 v[132:133], v[138:141], off offset:256
	s_nop 1
	v_or_b32_e32 v138, 16, v136
	v_ashrrev_i32_e32 v139, 31, v138
	v_lshlrev_b64 v[140:141], 12, v[138:139]
	v_add_co_u32_e32 v138, vcc, s0, v2
	v_lshl_add_u64 v[140:141], s[64:65], 0, v[140:141]
	s_nop 0
	v_addc_co_u32_e32 v139, vcc, 0, v3, vcc
	s_mov_b32 s0, 0x174000
	v_lshlrev_b32_e32 v0, 16, v164
	v_max_f32_e32 v0, v0, v0
	v_max_f32_e32 v146, 0x1e3ce508, v0
	v_and_b32_e32 v0, 0xffff0000, v164
	v_max_f32_e32 v0, v0, v0
	v_max_f32_e32 v147, 0x1e3ce508, v0
	v_lshlrev_b32_e32 v0, 16, v165
	v_max_f32_e32 v0, v0, v0
	v_max_f32_e32 v142, 0x1e3ce508, v0
	v_and_b32_e32 v0, 0xffff0000, v165
	v_max_f32_e32 v0, v0, v0
	v_max_f32_e32 v143, 0x1e3ce508, v0
	v_lshlrev_b32_e32 v0, 16, v166
	v_max_f32_e32 v0, v0, v0
	v_pk_mul_f32 v[148:149], v[122:123], v[142:143]
	v_max_f32_e32 v142, 0x1e3ce508, v0
	v_and_b32_e32 v0, 0xffff0000, v166
	v_max_f32_e32 v0, v0, v0
	v_max_f32_e32 v143, 0x1e3ce508, v0
	v_lshlrev_b32_e32 v0, 16, v167
	v_max_f32_e32 v0, v0, v0
	v_pk_mul_f32 v[150:151], v[116:117], v[142:143]
	v_max_f32_e32 v142, 0x1e3ce508, v0
	v_and_b32_e32 v0, 0xffff0000, v167
	v_max_f32_e32 v0, v0, v0
	v_pk_mul_f32 v[146:147], v[120:121], v[146:147]
	v_max_f32_e32 v143, 0x1e3ce508, v0
	v_pk_mul_f32 v[152:153], v[118:119], v[142:143]
	v_cvt_pk_bf16_f32 v142, v146, v147
	v_lshl_add_u64 v[146:147], v[140:141], 0, v[134:135]
	v_cvt_pk_bf16_f32 v143, v148, v149
	v_cvt_pk_bf16_f32 v144, v150, v151
	v_cvt_pk_bf16_f32 v145, v152, v153
	global_store_dwordx4 v[146:147], v[142:145], off
	v_lshlrev_b32_e32 v0, 16, v168
	v_max_f32_e32 v0, v0, v0
	v_max_f32_e32 v142, 0x1e3ce508, v0
	v_and_b32_e32 v0, 0xffff0000, v168
	v_max_f32_e32 v0, v0, v0
	v_max_f32_e32 v143, 0x1e3ce508, v0
	v_lshlrev_b32_e32 v0, 16, v169
	v_max_f32_e32 v0, v0, v0
	v_max_f32_e32 v138, 0x1e3ce508, v0
	v_and_b32_e32 v0, 0xffff0000, v169
	v_max_f32_e32 v0, v0, v0
	v_max_f32_e32 v139, 0x1e3ce508, v0
	v_lshlrev_b32_e32 v0, 16, v170
	v_max_f32_e32 v0, v0, v0
	v_pk_mul_f32 v[144:145], v[90:91], v[138:139]
	v_max_f32_e32 v138, 0x1e3ce508, v0
	v_and_b32_e32 v0, 0xffff0000, v170
	v_max_f32_e32 v0, v0, v0
	v_max_f32_e32 v139, 0x1e3ce508, v0
	v_lshlrev_b32_e32 v0, 16, v171
	v_max_f32_e32 v0, v0, v0
	v_pk_mul_f32 v[148:149], v[84:85], v[138:139]
	v_max_f32_e32 v138, 0x1e3ce508, v0
	v_and_b32_e32 v0, 0xffff0000, v171
	v_max_f32_e32 v0, v0, v0
	v_max_f32_e32 v139, 0x1e3ce508, v0
	v_pk_mul_f32 v[142:143], v[88:89], v[142:143]
	v_pk_mul_f32 v[150:151], v[86:87], v[138:139]
	v_cvt_pk_bf16_f32 v138, v142, v143
	v_cvt_pk_bf16_f32 v139, v144, v145
	v_cvt_pk_bf16_f32 v140, v148, v149
	v_cvt_pk_bf16_f32 v141, v150, v151
	global_store_dwordx4 v[146:147], v[138:141], off offset:256
	s_nop 1
	v_or_b32_e32 v138, 32, v136
	v_ashrrev_i32_e32 v139, 31, v138
	v_lshlrev_b64 v[140:141], 12, v[138:139]
	v_add_co_u32_e32 v138, vcc, s4, v2
	v_lshl_add_u64 v[140:141], s[64:65], 0, v[140:141]
	s_nop 0
	v_addc_co_u32_e32 v139, vcc, 0, v3, vcc
	v_or_b32_e32 v136, 48, v136
	v_ashrrev_i32_e32 v137, 31, v136
	v_lshlrev_b32_e32 v0, 16, v172
	v_max_f32_e32 v0, v0, v0
	v_max_f32_e32 v146, 0x1e3ce508, v0
	v_and_b32_e32 v0, 0xffff0000, v172
	v_max_f32_e32 v0, v0, v0
	v_max_f32_e32 v147, 0x1e3ce508, v0
	v_lshlrev_b32_e32 v0, 16, v173
	v_max_f32_e32 v0, v0, v0
	v_max_f32_e32 v142, 0x1e3ce508, v0
	v_and_b32_e32 v0, 0xffff0000, v173
	v_max_f32_e32 v0, v0, v0
	v_max_f32_e32 v143, 0x1e3ce508, v0
	v_lshlrev_b32_e32 v0, 16, v174
	v_max_f32_e32 v0, v0, v0
	v_pk_mul_f32 v[148:149], v[114:115], v[142:143]
	v_max_f32_e32 v142, 0x1e3ce508, v0
	v_and_b32_e32 v0, 0xffff0000, v174
	v_max_f32_e32 v0, v0, v0
	v_max_f32_e32 v143, 0x1e3ce508, v0
	v_lshlrev_b32_e32 v0, 16, v175
	v_max_f32_e32 v0, v0, v0
	v_pk_mul_f32 v[150:151], v[108:109], v[142:143]
	v_max_f32_e32 v142, 0x1e3ce508, v0
	v_and_b32_e32 v0, 0xffff0000, v175
	v_max_f32_e32 v0, v0, v0
	v_pk_mul_f32 v[146:147], v[112:113], v[146:147]
	v_max_f32_e32 v143, 0x1e3ce508, v0
	v_pk_mul_f32 v[152:153], v[110:111], v[142:143]
	v_cvt_pk_bf16_f32 v142, v146, v147
	v_lshl_add_u64 v[146:147], v[140:141], 0, v[134:135]
	v_cvt_pk_bf16_f32 v143, v148, v149
	v_cvt_pk_bf16_f32 v144, v150, v151
	v_cvt_pk_bf16_f32 v145, v152, v153
	global_store_dwordx4 v[146:147], v[142:145], off
	v_lshlrev_b32_e32 v0, 16, v176
	v_max_f32_e32 v0, v0, v0
	v_max_f32_e32 v142, 0x1e3ce508, v0
	v_and_b32_e32 v0, 0xffff0000, v176
	v_max_f32_e32 v0, v0, v0
	v_max_f32_e32 v143, 0x1e3ce508, v0
	v_lshlrev_b32_e32 v0, 16, v177
	v_max_f32_e32 v0, v0, v0
	v_max_f32_e32 v138, 0x1e3ce508, v0
	v_and_b32_e32 v0, 0xffff0000, v177
	v_max_f32_e32 v0, v0, v0
	v_max_f32_e32 v139, 0x1e3ce508, v0
	v_lshlrev_b32_e32 v0, 16, v178
	v_max_f32_e32 v0, v0, v0
	v_pk_mul_f32 v[144:145], v[82:83], v[138:139]
	v_max_f32_e32 v138, 0x1e3ce508, v0
	v_and_b32_e32 v0, 0xffff0000, v178
	v_max_f32_e32 v0, v0, v0
	v_max_f32_e32 v139, 0x1e3ce508, v0
	v_lshlrev_b32_e32 v0, 16, v179
	v_max_f32_e32 v0, v0, v0
	v_pk_mul_f32 v[148:149], v[76:77], v[138:139]
	v_max_f32_e32 v138, 0x1e3ce508, v0
	v_and_b32_e32 v0, 0xffff0000, v179
	v_max_f32_e32 v0, v0, v0
	v_max_f32_e32 v139, 0x1e3ce508, v0
	v_pk_mul_f32 v[142:143], v[80:81], v[142:143]
	v_pk_mul_f32 v[150:151], v[78:79], v[138:139]
	v_cvt_pk_bf16_f32 v138, v142, v143
	v_cvt_pk_bf16_f32 v139, v144, v145
	v_cvt_pk_bf16_f32 v140, v148, v149
	v_cvt_pk_bf16_f32 v141, v150, v151
	global_store_dwordx4 v[146:147], v[138:141], off offset:256
	s_nop 1
	v_lshlrev_b64 v[138:139], 12, v[136:137]
	v_add_co_u32_e32 v136, vcc, s0, v2
	v_lshl_add_u64 v[138:139], s[64:65], 0, v[138:139]
	s_nop 0
	v_addc_co_u32_e32 v137, vcc, 0, v3, vcc
	v_lshl_add_u64 v[138:139], v[138:139], 0, v[134:135]
	s_mov_b32 s0, 0x3e0000
	v_lshlrev_b32_e32 v0, 16, v180
	v_max_f32_e32 v0, v0, v0
	v_max_f32_e32 v144, 0x1e3ce508, v0
	v_and_b32_e32 v0, 0xffff0000, v180
	v_max_f32_e32 v0, v0, v0
	v_max_f32_e32 v145, 0x1e3ce508, v0
	v_lshlrev_b32_e32 v0, 16, v181
	v_max_f32_e32 v0, v0, v0
	v_max_f32_e32 v140, 0x1e3ce508, v0
	v_and_b32_e32 v0, 0xffff0000, v181
	v_max_f32_e32 v0, v0, v0
	v_max_f32_e32 v141, 0x1e3ce508, v0
	v_lshlrev_b32_e32 v0, 16, v182
	v_max_f32_e32 v0, v0, v0
	v_pk_mul_f32 v[146:147], v[106:107], v[140:141]
	v_max_f32_e32 v140, 0x1e3ce508, v0
	v_and_b32_e32 v0, 0xffff0000, v182
	v_max_f32_e32 v0, v0, v0
	v_max_f32_e32 v141, 0x1e3ce508, v0
	v_lshlrev_b32_e32 v0, 16, v183
	v_max_f32_e32 v0, v0, v0
	v_pk_mul_f32 v[148:149], v[100:101], v[140:141]
	v_max_f32_e32 v140, 0x1e3ce508, v0
	v_and_b32_e32 v0, 0xffff0000, v183
	v_max_f32_e32 v0, v0, v0
	v_max_f32_e32 v141, 0x1e3ce508, v0
	v_pk_mul_f32 v[144:145], v[104:105], v[144:145]
	v_pk_mul_f32 v[150:151], v[102:103], v[140:141]
	v_lshlrev_b32_e32 v0, 16, v184
	v_cvt_pk_bf16_f32 v140, v144, v145
	v_cvt_pk_bf16_f32 v141, v146, v147
	v_cvt_pk_bf16_f32 v142, v148, v149
	v_cvt_pk_bf16_f32 v143, v150, v151
	v_max_f32_e32 v0, v0, v0
	global_store_dwordx4 v[138:139], v[140:143], off
	s_nop 1
	v_max_f32_e32 v140, 0x1e3ce508, v0
	v_and_b32_e32 v0, 0xffff0000, v184
	v_max_f32_e32 v0, v0, v0
	v_max_f32_e32 v141, 0x1e3ce508, v0
	v_lshlrev_b32_e32 v0, 16, v185
	v_max_f32_e32 v0, v0, v0
	v_max_f32_e32 v134, 0x1e3ce508, v0
	v_and_b32_e32 v0, 0xffff0000, v185
	v_max_f32_e32 v0, v0, v0
	v_max_f32_e32 v135, 0x1e3ce508, v0
	v_lshlrev_b32_e32 v0, 16, v186
	v_max_f32_e32 v0, v0, v0
	v_pk_mul_f32 v[142:143], v[74:75], v[134:135]
	v_max_f32_e32 v134, 0x1e3ce508, v0
	v_and_b32_e32 v0, 0xffff0000, v186
	v_max_f32_e32 v0, v0, v0
	v_max_f32_e32 v135, 0x1e3ce508, v0
	v_lshlrev_b32_e32 v0, 16, v187
	v_max_f32_e32 v0, v0, v0
	v_pk_mul_f32 v[144:145], v[68:69], v[134:135]
	v_max_f32_e32 v134, 0x1e3ce508, v0
	v_and_b32_e32 v0, 0xffff0000, v187
	v_max_f32_e32 v0, v0, v0
	v_max_f32_e32 v135, 0x1e3ce508, v0
	v_pk_mul_f32 v[140:141], v[72:73], v[140:141]
	v_pk_mul_f32 v[146:147], v[70:71], v[134:135]
	v_cvt_pk_bf16_f32 v134, v140, v141
	v_cvt_pk_bf16_f32 v135, v142, v143
	v_cvt_pk_bf16_f32 v136, v144, v145
	v_cvt_pk_bf16_f32 v137, v146, v147
	global_store_dwordx4 v[138:139], v[134:137], off offset:256
	s_nop 1
	v_add_co_u32_e32 v134, vcc, s0, v2
	s_mov_b64 s[0:1], 0x80000
	s_nop 0
	v_addc_co_u32_e32 v135, vcc, 0, v3, vcc
	v_lshlrev_b32_e32 v0, 16, v188
	v_max_f32_e32 v0, v0, v0
	v_max_f32_e32 v140, 0x1e3ce508, v0
	v_and_b32_e32 v0, 0xffff0000, v188
	v_max_f32_e32 v0, v0, v0
	v_max_f32_e32 v141, 0x1e3ce508, v0
	v_lshlrev_b32_e32 v0, 16, v189
	v_max_f32_e32 v0, v0, v0
	v_max_f32_e32 v136, 0x1e3ce508, v0
	v_and_b32_e32 v0, 0xffff0000, v189
	v_max_f32_e32 v0, v0, v0
	v_max_f32_e32 v137, 0x1e3ce508, v0
	v_lshlrev_b32_e32 v0, 16, v190
	v_max_f32_e32 v0, v0, v0
	v_pk_mul_f32 v[142:143], v[66:67], v[136:137]
	v_max_f32_e32 v136, 0x1e3ce508, v0
	v_and_b32_e32 v0, 0xffff0000, v190
	v_max_f32_e32 v0, v0, v0
	v_max_f32_e32 v137, 0x1e3ce508, v0
	v_lshlrev_b32_e32 v0, 16, v191
	v_max_f32_e32 v0, v0, v0
	v_pk_mul_f32 v[144:145], v[60:61], v[136:137]
	v_max_f32_e32 v136, 0x1e3ce508, v0
	v_and_b32_e32 v0, 0xffff0000, v191
	v_max_f32_e32 v0, v0, v0
	v_max_f32_e32 v137, 0x1e3ce508, v0
	v_pk_mul_f32 v[140:141], v[64:65], v[140:141]
	v_pk_mul_f32 v[146:147], v[62:63], v[136:137]
	v_cvt_pk_bf16_f32 v137, v142, v143
	v_add_co_u32_e32 v142, vcc, s5, v132
	v_cvt_pk_bf16_f32 v136, v140, v141
	v_cvt_pk_bf16_f32 v138, v144, v145
	v_cvt_pk_bf16_f32 v139, v146, v147
	v_addc_co_u32_e32 v143, vcc, 0, v133, vcc
	global_store_dwordx4 v[142:143], v[136:139], off
	s_nop 1
	v_lshl_add_u64 v[140:141], v[132:133], 0, s[0:1]
	s_mov_b32 s0, 0x45c000
	v_lshlrev_b32_e32 v0, 16, v192
	v_max_f32_e32 v0, v0, v0
	v_max_f32_e32 v138, 0x1e3ce508, v0
	v_and_b32_e32 v0, 0xffff0000, v192
	v_max_f32_e32 v0, v0, v0
	v_max_f32_e32 v139, 0x1e3ce508, v0
	v_lshlrev_b32_e32 v0, 16, v193
	v_max_f32_e32 v0, v0, v0
	v_max_f32_e32 v134, 0x1e3ce508, v0
	v_and_b32_e32 v0, 0xffff0000, v193
	v_max_f32_e32 v0, v0, v0
	v_max_f32_e32 v135, 0x1e3ce508, v0
	v_lshlrev_b32_e32 v0, 16, v194
	v_max_f32_e32 v0, v0, v0
	v_pk_mul_f32 v[142:143], v[34:35], v[134:135]
	v_max_f32_e32 v134, 0x1e3ce508, v0
	v_and_b32_e32 v0, 0xffff0000, v194
	v_max_f32_e32 v0, v0, v0
	v_max_f32_e32 v135, 0x1e3ce508, v0
	v_lshlrev_b32_e32 v0, 16, v195
	v_max_f32_e32 v0, v0, v0
	v_pk_mul_f32 v[144:145], v[28:29], v[134:135]
	v_max_f32_e32 v134, 0x1e3ce508, v0
	v_and_b32_e32 v0, 0xffff0000, v195
	v_max_f32_e32 v0, v0, v0
	v_max_f32_e32 v135, 0x1e3ce508, v0
	v_pk_mul_f32 v[138:139], v[32:33], v[138:139]
	v_pk_mul_f32 v[146:147], v[30:31], v[134:135]
	v_cvt_pk_bf16_f32 v134, v138, v139
	v_cvt_pk_bf16_f32 v135, v142, v143
	v_cvt_pk_bf16_f32 v136, v144, v145
	v_cvt_pk_bf16_f32 v137, v146, v147
	global_store_dwordx4 v[140:141], v[134:137], off offset:256
	s_nop 1
	v_add_co_u32_e32 v134, vcc, s0, v2
	s_mov_b64 s[0:1], 0x90000
	s_nop 0
	v_addc_co_u32_e32 v135, vcc, 0, v3, vcc
	v_lshlrev_b32_e32 v0, 16, v210
	v_max_f32_e32 v0, v0, v0
	v_max_f32_e32 v140, 0x1e3ce508, v0
	v_and_b32_e32 v0, 0xffff0000, v210
	v_max_f32_e32 v0, v0, v0
	v_max_f32_e32 v141, 0x1e3ce508, v0
	v_lshlrev_b32_e32 v0, 16, v211
	v_max_f32_e32 v0, v0, v0
	v_max_f32_e32 v136, 0x1e3ce508, v0
	v_and_b32_e32 v0, 0xffff0000, v211
	v_max_f32_e32 v0, v0, v0
	v_max_f32_e32 v137, 0x1e3ce508, v0
	v_lshlrev_b32_e32 v0, 16, v212
	v_max_f32_e32 v0, v0, v0
	v_pk_mul_f32 v[142:143], v[58:59], v[136:137]
	v_max_f32_e32 v136, 0x1e3ce508, v0
	v_and_b32_e32 v0, 0xffff0000, v212
	v_max_f32_e32 v0, v0, v0
	v_max_f32_e32 v137, 0x1e3ce508, v0
	v_lshlrev_b32_e32 v0, 16, v213
	v_max_f32_e32 v0, v0, v0
	v_pk_mul_f32 v[144:145], v[52:53], v[136:137]
	v_max_f32_e32 v136, 0x1e3ce508, v0
	v_and_b32_e32 v0, 0xffff0000, v213
	v_max_f32_e32 v0, v0, v0
	v_max_f32_e32 v137, 0x1e3ce508, v0
	v_pk_mul_f32 v[140:141], v[56:57], v[140:141]
	v_pk_mul_f32 v[146:147], v[54:55], v[136:137]
	v_cvt_pk_bf16_f32 v137, v142, v143
	v_add_co_u32_e32 v142, vcc, s6, v132
	v_cvt_pk_bf16_f32 v136, v140, v141
	v_cvt_pk_bf16_f32 v138, v144, v145
	v_cvt_pk_bf16_f32 v139, v146, v147
	v_addc_co_u32_e32 v143, vcc, 0, v133, vcc
	global_store_dwordx4 v[142:143], v[136:139], off
	s_nop 1
	v_lshl_add_u64 v[140:141], v[132:133], 0, s[0:1]
	s_mov_b32 s0, 0x4d8000
	v_lshlrev_b32_e32 v0, 16, v214
	v_max_f32_e32 v0, v0, v0
	v_max_f32_e32 v138, 0x1e3ce508, v0
	v_and_b32_e32 v0, 0xffff0000, v214
	v_max_f32_e32 v0, v0, v0
	v_max_f32_e32 v139, 0x1e3ce508, v0
	v_lshlrev_b32_e32 v0, 16, v215
	v_max_f32_e32 v0, v0, v0
	v_max_f32_e32 v134, 0x1e3ce508, v0
	v_and_b32_e32 v0, 0xffff0000, v215
	v_max_f32_e32 v0, v0, v0
	v_max_f32_e32 v135, 0x1e3ce508, v0
	v_lshlrev_b32_e32 v0, 16, v216
	v_max_f32_e32 v0, v0, v0
	v_pk_mul_f32 v[142:143], v[26:27], v[134:135]
	v_max_f32_e32 v134, 0x1e3ce508, v0
	v_and_b32_e32 v0, 0xffff0000, v216
	v_max_f32_e32 v0, v0, v0
	v_max_f32_e32 v135, 0x1e3ce508, v0
	v_lshlrev_b32_e32 v0, 16, v217
	v_max_f32_e32 v0, v0, v0
	v_pk_mul_f32 v[144:145], v[20:21], v[134:135]
	v_max_f32_e32 v134, 0x1e3ce508, v0
	v_and_b32_e32 v0, 0xffff0000, v217
	v_max_f32_e32 v0, v0, v0
	v_max_f32_e32 v135, 0x1e3ce508, v0
	v_pk_mul_f32 v[138:139], v[24:25], v[138:139]
	v_pk_mul_f32 v[146:147], v[22:23], v[134:135]
	v_cvt_pk_bf16_f32 v134, v138, v139
	v_cvt_pk_bf16_f32 v135, v142, v143
	v_cvt_pk_bf16_f32 v136, v144, v145
	v_cvt_pk_bf16_f32 v137, v146, v147
	global_store_dwordx4 v[140:141], v[134:137], off offset:256
	s_nop 1
	v_add_co_u32_e32 v134, vcc, s0, v2
	s_mov_b64 s[0:1], 0xa0000
	s_nop 0
	v_addc_co_u32_e32 v135, vcc, 0, v3, vcc
	v_lshlrev_b32_e32 v0, 16, v228
	v_max_f32_e32 v0, v0, v0
	v_max_f32_e32 v140, 0x1e3ce508, v0
	v_and_b32_e32 v0, 0xffff0000, v228
	v_max_f32_e32 v0, v0, v0
	v_max_f32_e32 v141, 0x1e3ce508, v0
	v_lshlrev_b32_e32 v0, 16, v229
	v_max_f32_e32 v0, v0, v0
	v_max_f32_e32 v136, 0x1e3ce508, v0
	v_and_b32_e32 v0, 0xffff0000, v229
	v_max_f32_e32 v0, v0, v0
	v_max_f32_e32 v137, 0x1e3ce508, v0
	v_lshlrev_b32_e32 v0, 16, v230
	v_max_f32_e32 v0, v0, v0
	v_pk_mul_f32 v[142:143], v[50:51], v[136:137]
	v_max_f32_e32 v136, 0x1e3ce508, v0
	v_and_b32_e32 v0, 0xffff0000, v230
	v_max_f32_e32 v0, v0, v0
	v_max_f32_e32 v137, 0x1e3ce508, v0
	v_lshlrev_b32_e32 v0, 16, v231
	v_max_f32_e32 v0, v0, v0
	v_pk_mul_f32 v[144:145], v[44:45], v[136:137]
	v_max_f32_e32 v136, 0x1e3ce508, v0
	v_and_b32_e32 v0, 0xffff0000, v231
	v_max_f32_e32 v0, v0, v0
	v_max_f32_e32 v137, 0x1e3ce508, v0
	v_pk_mul_f32 v[140:141], v[48:49], v[140:141]
	v_pk_mul_f32 v[146:147], v[46:47], v[136:137]
	v_cvt_pk_bf16_f32 v137, v142, v143
	v_add_co_u32_e32 v142, vcc, s7, v132
	v_cvt_pk_bf16_f32 v136, v140, v141
	v_cvt_pk_bf16_f32 v138, v144, v145
	v_cvt_pk_bf16_f32 v139, v146, v147
	v_addc_co_u32_e32 v143, vcc, 0, v133, vcc
	global_store_dwordx4 v[142:143], v[136:139], off
	s_nop 1
	v_lshl_add_u64 v[140:141], v[132:133], 0, s[0:1]
	s_mov_b32 s0, 0x554000
	v_lshlrev_b32_e32 v0, 16, v242
	v_max_f32_e32 v0, v0, v0
	v_max_f32_e32 v138, 0x1e3ce508, v0
	v_and_b32_e32 v0, 0xffff0000, v242
	v_max_f32_e32 v0, v0, v0
	v_max_f32_e32 v139, 0x1e3ce508, v0
	v_lshlrev_b32_e32 v0, 16, v243
	v_max_f32_e32 v0, v0, v0
	v_max_f32_e32 v134, 0x1e3ce508, v0
	v_and_b32_e32 v0, 0xffff0000, v243
	v_max_f32_e32 v0, v0, v0
	v_max_f32_e32 v135, 0x1e3ce508, v0
	v_lshlrev_b32_e32 v0, 16, v244
	v_max_f32_e32 v0, v0, v0
	v_pk_mul_f32 v[142:143], v[18:19], v[134:135]
	v_max_f32_e32 v134, 0x1e3ce508, v0
	v_and_b32_e32 v0, 0xffff0000, v244
	v_max_f32_e32 v0, v0, v0
	v_max_f32_e32 v135, 0x1e3ce508, v0
	v_lshlrev_b32_e32 v0, 16, v245
	v_max_f32_e32 v0, v0, v0
	v_pk_mul_f32 v[144:145], v[12:13], v[134:135]
	v_max_f32_e32 v134, 0x1e3ce508, v0
	v_and_b32_e32 v0, 0xffff0000, v245
	v_max_f32_e32 v0, v0, v0
	v_max_f32_e32 v135, 0x1e3ce508, v0
	v_pk_mul_f32 v[138:139], v[16:17], v[138:139]
	v_pk_mul_f32 v[146:147], v[14:15], v[134:135]
	v_cvt_pk_bf16_f32 v134, v138, v139
	v_cvt_pk_bf16_f32 v135, v142, v143
	v_cvt_pk_bf16_f32 v136, v144, v145
	v_cvt_pk_bf16_f32 v137, v146, v147
	global_store_dwordx4 v[140:141], v[134:137], off offset:256
	s_nop 1
	v_add_co_u32_e32 v136, vcc, s0, v2
	s_mov_b64 s[0:1], 0xb0000
	s_nop 0
	v_addc_co_u32_e32 v137, vcc, 0, v3, vcc
	v_lshlrev_b32_e32 v0, 16, v246
	v_max_f32_e32 v0, v0, v0
	v_max_f32_e32 v134, 0x1e3ce508, v0
	v_and_b32_e32 v0, 0xffff0000, v246
	v_max_f32_e32 v0, v0, v0
	v_max_f32_e32 v135, 0x1e3ce508, v0
	v_lshlrev_b32_e32 v0, 16, v247
	v_max_f32_e32 v0, v0, v0
	v_max_f32_e32 v138, 0x1e3ce508, v0
	v_and_b32_e32 v0, 0xffff0000, v247
	v_max_f32_e32 v0, v0, v0
	v_max_f32_e32 v139, 0x1e3ce508, v0
	v_lshlrev_b32_e32 v0, 16, v248
	v_max_f32_e32 v0, v0, v0
	v_pk_mul_f32 v[142:143], v[42:43], v[138:139]
	v_max_f32_e32 v138, 0x1e3ce508, v0
	v_and_b32_e32 v0, 0xffff0000, v248
	v_max_f32_e32 v0, v0, v0
	v_max_f32_e32 v139, 0x1e3ce508, v0
	v_lshlrev_b32_e32 v0, 16, v249
	v_max_f32_e32 v0, v0, v0
	v_pk_mul_f32 v[144:145], v[36:37], v[138:139]
	v_max_f32_e32 v138, 0x1e3ce508, v0
	v_and_b32_e32 v0, 0xffff0000, v249
	v_max_f32_e32 v0, v0, v0
	v_pk_mul_f32 v[134:135], v[40:41], v[134:135]
	v_max_f32_e32 v139, 0x1e3ce508, v0
	v_pk_mul_f32 v[146:147], v[38:39], v[138:139]
	v_cvt_pk_bf16_f32 v138, v134, v135
	v_lshl_add_u64 v[134:135], v[132:133], 0, s[0:1]
	v_add_co_u32_e32 v132, vcc, s8, v132
	v_cvt_pk_bf16_f32 v139, v142, v143
	v_cvt_pk_bf16_f32 v140, v144, v145
	v_cvt_pk_bf16_f32 v141, v146, v147
	v_addc_co_u32_e32 v133, vcc, 0, v133, vcc
	global_store_dwordx4 v[132:133], v[138:141], off
	s_nop 1
	s_waitcnt vmcnt(15)
	v_lshlrev_b32_e32 v0, 16, v156
	v_max_f32_e32 v0, v0, v0
	v_max_f32_e32 v132, 0x1e3ce508, v0
	v_and_b32_e32 v0, 0xffff0000, v156
	v_max_f32_e32 v0, v0, v0
	v_max_f32_e32 v133, 0x1e3ce508, v0
	v_lshlrev_b32_e32 v0, 16, v157
	v_max_f32_e32 v0, v0, v0
	v_max_f32_e32 v136, 0x1e3ce508, v0
	v_and_b32_e32 v0, 0xffff0000, v157
	v_max_f32_e32 v0, v0, v0
	v_max_f32_e32 v137, 0x1e3ce508, v0
	v_lshlrev_b32_e32 v0, 16, v158
	v_max_f32_e32 v0, v0, v0
	v_pk_mul_f32 v[140:141], v[10:11], v[136:137]
	v_max_f32_e32 v136, 0x1e3ce508, v0
	v_and_b32_e32 v0, 0xffff0000, v158
	v_max_f32_e32 v0, v0, v0
	v_max_f32_e32 v137, 0x1e3ce508, v0
	v_lshlrev_b32_e32 v0, 16, v159
	v_max_f32_e32 v0, v0, v0
	v_pk_mul_f32 v[142:143], v[4:5], v[136:137]
	v_max_f32_e32 v136, 0x1e3ce508, v0
	v_and_b32_e32 v0, 0xffff0000, v159
	v_max_f32_e32 v0, v0, v0
	v_max_f32_e32 v137, 0x1e3ce508, v0
	v_pk_mul_f32 v[132:133], v[8:9], v[132:133]
	v_pk_mul_f32 v[144:145], v[6:7], v[136:137]
	v_cvt_pk_bf16_f32 v136, v132, v133
	v_cvt_pk_bf16_f32 v137, v140, v141
	v_cvt_pk_bf16_f32 v138, v142, v143
	v_cvt_pk_bf16_f32 v139, v144, v145
	global_store_dwordx4 v[134:135], v[136:139], off offset:256
	s_cbranch_execz .LBB0_1240
